# SCAN1 image sharing, P-role wave releases the partner's images right after its last LDS read (state update overlaps the partner's next image build)
# speedup vs baseline: 1.0016x; 1.0016x over previous
; template <int role> __device__ __forceinline__ void ph_scan1m_r(Ctx& C) {
;     ...
;         int lane_e = lane0; asm volatile("" : "+v"(lane_e));
;         float* pp = g_pu + (((size_t)chain * NCK + chunk) * 2 + role) * 4096 + (lane_e & 31) * 64 + 4 * (lane_e >> 5);
; #pragma unroll
;         for (int kt = 0; kt < 2; ++kt)
; #pragma unroll
;             for (int ct = 0; ct < 2; ++ct)
; #pragma unroll
;                 for (int g = 0; g < 4; ++g) *(f32x4*)(pp + (32 * ct) * 64 + 32 * kt + 8 * g) = (f32x4){st[kt][ct][4 * g], st[kt][ct][4 * g + 1], st[kt][ct][4 * g + 2], st[kt][ct][4 * g + 3]};
.LBB0_704:
	s_barrier
	s_ashr_i32 s27, s26, 31
	s_ashr_i32 s29, s28, 31
	s_lshl_b64 s[0:1], s[26:27], 20
	v_mov_b32_e32 v66, v140
	s_add_u32 s2, s57, s0
	s_addc_u32 s3, s58, s1
	s_lshl_b64 s[0:1], s[28:29], 15
	s_add_u32 s0, s2, s0
	v_lshlrev_b32_e32 v64, 8, v66
	v_ashrrev_i32_e32 v66, 3, v66
	s_addc_u32 s1, s3, s1
	v_and_b32_e32 v112, 0x1f00, v64
	v_and_b32_e32 v66, -4, v66
	v_lshl_add_u64 v[64:65], s[0:1], 0, v[112:113]
	v_ashrrev_i32_e32 v67, 31, v66
	v_lshl_add_u64 v[64:65], v[66:67], 2, v[64:65]
	global_store_dwordx4 v[64:65], v[0:3], off
	global_store_dwordx4 v[64:65], v[4:7], off offset:32
	global_store_dwordx4 v[64:65], v[8:11], off offset:64
	global_store_dwordx4 v[64:65], v[12:15], off offset:96
	v_add_co_u32_e32 v0, vcc, s69, v64
	s_nop 1
	v_addc_co_u32_e32 v1, vcc, 0, v65, vcc
	global_store_dwordx4 v[0:1], v[48:51], off
	global_store_dwordx4 v[0:1], v[52:55], off offset:32
	global_store_dwordx4 v[0:1], v[56:59], off offset:64
	global_store_dwordx4 v[0:1], v[60:63], off offset:96
	global_store_dwordx4 v[64:65], v[32:35], off offset:128
	global_store_dwordx4 v[64:65], v[36:39], off offset:160
	global_store_dwordx4 v[64:65], v[40:43], off offset:192
	global_store_dwordx4 v[64:65], v[44:47], off offset:224
	global_store_dwordx4 v[0:1], v[16:19], off offset:128
	global_store_dwordx4 v[0:1], v[20:23], off offset:160
	global_store_dwordx4 v[0:1], v[24:27], off offset:192
	global_store_dwordx4 v[0:1], v[28:31], off offset:224

; template <int role> __device__ __forceinline__ void ph_scan1m_r(Ctx& C) {
;     ...
;     for (int base = C.bid * 4; base < nitems; base += C.nb * 4) {
;         const int item = base + itl; if (item >= nitems) continue;
;         const int chain = item / NCK, chunk = item % NCK, z = chain >> 4, h = chain & 15; const size_t zoff = (size_t)z * S * RW; const f32x2 ka2 = *(const f32x2*)(k_a + h * 64 + 2 * (lane0 & 31)), k1 = (f32x2){1.0f - ka2.x, 1.0f - ka2.y};
;         f32x16 st[2][2];
;         { int lane_s = lane0; asm volatile("" : "+v"(lane_s)); const int r31s = lane_s & 31, hhs = lane_s >> 5;
; #pragma unroll
;         for (int kt = 0; kt < 2; ++kt)
; #pragma unroll
;             for (int ct = 0; ct < 2; ++ct)
; #pragma unroll
;                 for (int e = 0; e < 16; ++e) st[kt][ct][e] = (role == 0 && (32 * kt + (e & 3) + 8 * (e >> 2) + 4 * hhs) == (32 * ct + r31s)) ? 1.f : 0.f; }
;         unsigned rl[8], rn[8], ra[8], rk[8], rr_[8], rv[8];
;     ...
;         SM_LOADRAW(0);
.LBB0_717:
	s_or_b32 s0, s51, s92
	s_cmpk_gt_i32 s0, 0x3ff
	s_cbranch_scc1 .LBB0_716
	s_ashr_i32 s1, s0, 31
	s_lshr_b32 s1, s1, 27
	s_add_i32 s4, s0, s1
	s_ashr_i32 s24, s4, 5
	s_ashr_i32 s2, s4, 9
	s_andn2_b32 s4, s4, 31
	s_sub_i32 s26, s0, s4
	s_lshl_b32 s1, s24, 6
	s_lshl_b32 s25, s26, 9
	s_ashr_i32 s3, s2, 31
	s_and_b32 s1, s1, 0x3c0
	s_sub_i32 s6, 0x3fff, s25
	s_cmp_lt_u32 s24, 16
	s_cselect_b64 s[28:29], -1, 0
	s_and_b64 s[4:5], s[28:29], exec
	s_cselect_b32 s4, s25, s6
	s_cselect_b32 s31, 0, -1
	s_cselect_b32 s30, s53, 0xfffffc00
	s_ashr_i32 s5, s4, 31
	s_lshl_b64 s[2:3], s[2:3], 25
	s_add_u32 s27, s39, s2
	s_addc_u32 s59, s43, s3
	s_lshl_b64 s[10:11], s[4:5], 11
	s_lshl_b32 s12, s1, 1
	s_or_b32 s10, s10, s12
	s_add_u32 s4, s27, s10
	s_addc_u32 s5, s59, s11
	s_add_u32 s6, s40, s10
	s_addc_u32 s7, s41, s11
	s_add_u32 s60, s44, s2
	s_addc_u32 s61, s45, s3
	s_add_u32 s8, s60, s10
	v_mov_b32_e32 v0, v124
	v_mov_b32_e32 v35, v124
	s_addc_u32 s9, s61, s11
	s_add_u32 s10, s23, s10
	v_ashrrev_i32_e32 v46, 5, v35
	v_lshlrev_b32_e32 v35, 1, v35
	s_addc_u32 s11, s38, s11
	s_lshl_b64 s[34:35], s[30:31], 1
	v_and_b32_e32 v35, 62, v35
	v_mad_i64_i32 v[36:37], s[14:15], s30, v46, 0
	v_mov_b64_e32 v[44:45], s[34:35]
	v_or_b32_e32 v36, v36, v35
	v_mad_i64_i32 v[44:45], s[14:15], s30, v46, v[44:45]
	v_lshlrev_b64 v[36:37], 1, v[36:37]
	v_or_b32_e32 v46, v44, v35
	v_mov_b32_e32 v47, v45
	v_lshl_add_u64 v[38:39], s[4:5], 0, v[36:37]
	v_lshl_add_u64 v[40:41], s[6:7], 0, v[36:37]
	v_lshl_add_u64 v[42:43], s[8:9], 0, v[36:37]
	v_lshl_add_u64 v[36:37], s[10:11], 0, v[36:37]
	v_lshlrev_b64 v[46:47], 1, v[46:47]
	v_lshl_add_u64 v[48:49], s[4:5], 0, v[46:47]
	v_lshl_add_u64 v[50:51], s[6:7], 0, v[46:47]
	v_lshl_add_u64 v[52:53], s[8:9], 0, v[46:47]
	v_lshl_add_u64 v[46:47], s[10:11], 0, v[46:47]
	global_load_dword v126, v[38:39], off
	global_load_dword v127, v[40:41], off
	global_load_dword v128, v[42:43], off
	global_load_dword v129, v[36:37], off
	global_load_dword v130, v[48:49], off
	global_load_dword v131, v[50:51], off
	global_load_dword v132, v[52:53], off
	global_load_dword v133, v[46:47], off
	v_lshl_add_u64 v[36:37], v[44:45], 0, s[34:35]
	v_or_b32_e32 v38, v36, v35
	v_mov_b32_e32 v39, v37
	v_lshl_add_u64 v[36:37], v[36:37], 0, s[34:35]
	v_lshlrev_b64 v[38:39], 1, v[38:39]
	v_or_b32_e32 v46, v36, v35
	v_mov_b32_e32 v47, v37
	v_lshl_add_u64 v[40:41], s[4:5], 0, v[38:39]
	v_lshl_add_u64 v[42:43], s[6:7], 0, v[38:39]
	v_lshl_add_u64 v[44:45], s[8:9], 0, v[38:39]
	v_lshl_add_u64 v[38:39], s[10:11], 0, v[38:39]
	v_lshlrev_b64 v[46:47], 1, v[46:47]
	v_lshl_add_u64 v[36:37], v[36:37], 0, s[34:35]
	v_lshl_add_u64 v[48:49], s[4:5], 0, v[46:47]
	v_lshl_add_u64 v[50:51], s[6:7], 0, v[46:47]
	v_lshl_add_u64 v[52:53], s[8:9], 0, v[46:47]
	v_lshl_add_u64 v[46:47], s[10:11], 0, v[46:47]
	global_load_dword v134, v[40:41], off
	global_load_dword v135, v[42:43], off
	global_load_dword v136, v[44:45], off
	global_load_dword v137, v[38:39], off
	global_load_dword v138, v[48:49], off
	global_load_dword v139, v[50:51], off
	global_load_dword v140, v[52:53], off
	global_load_dword v141, v[46:47], off
	v_or_b32_e32 v38, v36, v35
	v_mov_b32_e32 v39, v37
	v_lshl_add_u64 v[36:37], v[36:37], 0, s[34:35]
	v_lshlrev_b64 v[38:39], 1, v[38:39]
	v_or_b32_e32 v46, v36, v35
	v_mov_b32_e32 v47, v37
	v_lshl_add_u64 v[40:41], s[4:5], 0, v[38:39]
	v_lshl_add_u64 v[42:43], s[6:7], 0, v[38:39]
	v_lshl_add_u64 v[44:45], s[8:9], 0, v[38:39]
	v_lshl_add_u64 v[38:39], s[10:11], 0, v[38:39]
	v_lshlrev_b64 v[46:47], 1, v[46:47]
	v_lshl_add_u64 v[36:37], v[36:37], 0, s[34:35]
	v_lshl_add_u64 v[48:49], s[4:5], 0, v[46:47]
	v_lshl_add_u64 v[50:51], s[6:7], 0, v[46:47]
	v_lshl_add_u64 v[52:53], s[8:9], 0, v[46:47]
	v_lshl_add_u64 v[46:47], s[10:11], 0, v[46:47]
	global_load_dword v142, v[40:41], off
	global_load_dword v143, v[42:43], off
	global_load_dword v144, v[44:45], off
	global_load_dword v145, v[38:39], off
	global_load_dword v146, v[48:49], off
	global_load_dword v147, v[50:51], off
	global_load_dword v148, v[52:53], off
	global_load_dword v149, v[46:47], off
	v_or_b32_e32 v38, v36, v35
	v_mov_b32_e32 v39, v37
	v_lshl_add_u64 v[36:37], v[36:37], 0, s[34:35]
	v_lshlrev_b64 v[38:39], 1, v[38:39]
	v_or_b32_e32 v36, v36, v35
	v_lshl_add_u64 v[40:41], s[4:5], 0, v[38:39]
	v_lshlrev_b64 v[36:37], 1, v[36:37]
	v_lshl_add_u64 v[42:43], s[6:7], 0, v[38:39]
	v_lshl_add_u64 v[44:45], s[8:9], 0, v[38:39]
	v_lshl_add_u64 v[38:39], s[10:11], 0, v[38:39]
	v_lshl_add_u64 v[46:47], s[4:5], 0, v[36:37]
	v_lshl_add_u64 v[48:49], s[6:7], 0, v[36:37]
	v_lshl_add_u64 v[50:51], s[8:9], 0, v[36:37]
	v_lshl_add_u64 v[36:37], s[10:11], 0, v[36:37]
	global_load_dword v150, v[40:41], off
	global_load_dword v151, v[42:43], off
	global_load_dword v152, v[44:45], off
	global_load_dword v153, v[38:39], off
	global_load_dword v154, v[46:47], off
	global_load_dword v155, v[48:49], off
	global_load_dword v156, v[50:51], off
	global_load_dword v157, v[36:37], off
	v_ashrrev_i32_e32 v3, 3, v0
	v_and_b32_e32 v54, 31, v0
	v_and_b32_e32 v55, -4, v3
	v_cmp_eq_u32_e32 vcc, v55, v54
	v_or_b32_e32 v17, 1, v55
	v_or_b32_e32 v18, 2, v55
	v_cndmask_b32_e64 v0, 0, 1.0, vcc
	v_cmp_eq_u32_e32 vcc, v17, v54
	v_or_b32_e32 v19, 3, v3
	v_add_u32_e32 v20, 8, v55
	v_cndmask_b32_e64 v1, 0, 1.0, vcc
	v_cmp_eq_u32_e32 vcc, v18, v54
	v_add_u32_e32 v21, 9, v55
	v_add_u32_e32 v22, 10, v55
	v_cndmask_b32_e64 v2, 0, 1.0, vcc
	v_cmp_eq_u32_e32 vcc, v19, v54
	v_add_u32_e32 v23, 8, v19
	v_add_u32_e32 v24, 16, v55
	v_cndmask_b32_e64 v3, 0, 1.0, vcc
	v_cmp_eq_u32_e32 vcc, v20, v54
	v_add_u32_e32 v25, 17, v55
	v_add_u32_e32 v26, 18, v55
	v_cndmask_b32_e64 v4, 0, 1.0, vcc
; template <int role> __device__ __forceinline__ void ph_scan1m_r(Ctx& C) {
;     ...
;         { int lane_s = lane0; asm volatile("" : "+v"(lane_s)); const int r31s = lane_s & 31, hhs = lane_s >> 5;
; #pragma unroll
;         for (int kt = 0; kt < 2; ++kt)
; #pragma unroll
;             for (int ct = 0; ct < 2; ++ct)
; #pragma unroll
;                 for (int e = 0; e < 16; ++e) st[kt][ct][e] = (role == 0 && (32 * kt + (e & 3) + 8 * (e >> 2) + 4 * hhs) == (32 * ct + r31s)) ? 1.f : 0.f; }
	v_cmp_eq_u32_e32 vcc, v21, v54
	v_add_u32_e32 v27, 16, v19
	v_add_u32_e32 v28, 24, v55
	v_cndmask_b32_e64 v5, 0, 1.0, vcc
	v_cmp_eq_u32_e32 vcc, v22, v54
	v_add_u32_e32 v29, 25, v55
	v_add_u32_e32 v30, 26, v55
	v_cndmask_b32_e64 v6, 0, 1.0, vcc
	v_cmp_eq_u32_e32 vcc, v23, v54
	v_add_u32_e32 v31, 24, v19
	v_or_b32_e32 v63, 32, v54
	v_cndmask_b32_e64 v7, 0, 1.0, vcc
	v_cmp_eq_u32_e32 vcc, v24, v54
	v_add_u32_e32 v32, 32, v55
	v_add_u32_e32 v56, 33, v55
	v_cndmask_b32_e64 v8, 0, 1.0, vcc
	v_cmp_eq_u32_e32 vcc, v25, v54
	v_add_u32_e32 v57, 34, v55
	v_add_u32_e32 v58, 35, v55
	v_cndmask_b32_e64 v9, 0, 1.0, vcc
	v_cmp_eq_u32_e32 vcc, v26, v54
	v_add_u32_e32 v48, 40, v55
	v_add_u32_e32 v53, 41, v55
	v_cndmask_b32_e64 v10, 0, 1.0, vcc
	v_cmp_eq_u32_e32 vcc, v27, v54
	v_add_u32_e32 v59, 42, v55
	v_add_u32_e32 v60, 43, v55
	v_cndmask_b32_e64 v11, 0, 1.0, vcc
	v_cmp_eq_u32_e32 vcc, v28, v54
	v_add_u32_e32 v61, 48, v55
	v_add_u32_e32 v62, 49, v55
	v_cndmask_b32_e64 v12, 0, 1.0, vcc
	v_cmp_eq_u32_e32 vcc, v29, v54
	v_add_u32_e32 v64, 50, v55
	v_add_u32_e32 v65, 51, v55
	v_cndmask_b32_e64 v13, 0, 1.0, vcc
	v_cmp_eq_u32_e32 vcc, v30, v54
	v_add_u32_e32 v66, 56, v55
	v_add_u32_e32 v67, 57, v55
	v_cndmask_b32_e64 v14, 0, 1.0, vcc
	v_cmp_eq_u32_e32 vcc, v31, v54
	v_add_u32_e32 v68, 58, v55
	v_add_u32_e32 v69, 59, v55
	v_cndmask_b32_e64 v15, 0, 1.0, vcc
	v_cmp_eq_u32_e32 vcc, v55, v63
	s_add_u32 s2, s46, s2
	s_addc_u32 s3, s47, s3
	v_cndmask_b32_e64 v16, 0, 1.0, vcc
	v_cmp_eq_u32_e32 vcc, v17, v63
	s_add_u32 s63, s2, s12
	s_addc_u32 s64, s3, 0
	v_cndmask_b32_e64 v17, 0, 1.0, vcc
	v_cmp_eq_u32_e32 vcc, v18, v63
	s_lshl_b32 s2, s24, 14
	s_lshl_b32 s0, s0, 9
	v_cndmask_b32_e64 v18, 0, 1.0, vcc
	v_cmp_eq_u32_e32 vcc, v19, v63
	s_sub_i32 s0, s2, s0
	s_mov_b32 s62, 0
	v_cndmask_b32_e64 v19, 0, 1.0, vcc
	v_cmp_eq_u32_e32 vcc, v20, v63
	s_add_i32 s65, s0, 0x3fef
	s_lshl_b32 s66, s1, 1
	v_cndmask_b32_e64 v20, 0, 1.0, vcc
	v_cmp_eq_u32_e32 vcc, v21, v63
	s_nop 1
	v_cndmask_b32_e64 v21, 0, 1.0, vcc
	v_cmp_eq_u32_e32 vcc, v22, v63
	s_nop 1
	v_cndmask_b32_e64 v22, 0, 1.0, vcc
	v_cmp_eq_u32_e32 vcc, v23, v63
	s_nop 1
	v_cndmask_b32_e64 v23, 0, 1.0, vcc
	v_cmp_eq_u32_e32 vcc, v24, v63
	s_nop 1
	v_cndmask_b32_e64 v24, 0, 1.0, vcc
	v_cmp_eq_u32_e32 vcc, v25, v63
	s_nop 1
	v_cndmask_b32_e64 v25, 0, 1.0, vcc
	v_cmp_eq_u32_e32 vcc, v26, v63
	s_nop 1
	v_cndmask_b32_e64 v26, 0, 1.0, vcc
	v_cmp_eq_u32_e32 vcc, v27, v63
	s_nop 1
	v_cndmask_b32_e64 v27, 0, 1.0, vcc
	v_cmp_eq_u32_e32 vcc, v28, v63
	s_nop 1
	v_cndmask_b32_e64 v28, 0, 1.0, vcc
	v_cmp_eq_u32_e32 vcc, v29, v63
	s_nop 1
	v_cndmask_b32_e64 v29, 0, 1.0, vcc
	v_cmp_eq_u32_e32 vcc, v30, v63
	s_nop 1
	v_cndmask_b32_e64 v30, 0, 1.0, vcc
	v_cmp_eq_u32_e32 vcc, v31, v63
	s_nop 1
	v_cndmask_b32_e64 v31, 0, 1.0, vcc
	v_cmp_eq_u32_e32 vcc, v32, v54
	s_nop 1
	v_cndmask_b32_e64 v32, 0, 1.0, vcc
	v_cmp_eq_u32_e32 vcc, v56, v54
	s_nop 1
	v_cndmask_b32_e64 v33, 0, 1.0, vcc
	v_cmp_eq_u32_e32 vcc, v57, v54
	s_nop 1
	v_cndmask_b32_e64 v34, 0, 1.0, vcc
	v_cmp_eq_u32_e32 vcc, v58, v54
	s_nop 1
	v_cndmask_b32_e64 v35, 0, 1.0, vcc
	v_cmp_eq_u32_e32 vcc, v48, v54
	s_nop 1
	v_cndmask_b32_e64 v36, 0, 1.0, vcc
	v_cmp_eq_u32_e32 vcc, v53, v54
	s_nop 1
	v_cndmask_b32_e64 v37, 0, 1.0, vcc
	v_cmp_eq_u32_e32 vcc, v59, v54
	s_nop 1
	v_cndmask_b32_e64 v38, 0, 1.0, vcc
	v_cmp_eq_u32_e32 vcc, v60, v54
	s_nop 1
	v_cndmask_b32_e64 v39, 0, 1.0, vcc
	v_cmp_eq_u32_e32 vcc, v61, v54
	s_nop 1
	v_cndmask_b32_e64 v40, 0, 1.0, vcc
	v_cmp_eq_u32_e32 vcc, v62, v54
	s_nop 1
	v_cndmask_b32_e64 v41, 0, 1.0, vcc
	v_cmp_eq_u32_e32 vcc, v64, v54
	s_nop 1
	v_cndmask_b32_e64 v42, 0, 1.0, vcc
	v_cmp_eq_u32_e32 vcc, v65, v54
	s_nop 1
	v_cndmask_b32_e64 v43, 0, 1.0, vcc
	v_cmp_eq_u32_e32 vcc, v66, v54
	s_nop 1
	v_cndmask_b32_e64 v44, 0, 1.0, vcc
	v_cmp_eq_u32_e32 vcc, v67, v54
	s_nop 1
	v_cndmask_b32_e64 v45, 0, 1.0, vcc
	v_cmp_eq_u32_e32 vcc, v68, v54
	s_nop 1
	v_cndmask_b32_e64 v46, 0, 1.0, vcc
	v_cmp_eq_u32_e32 vcc, v69, v54
	s_nop 1
	v_cndmask_b32_e64 v47, 0, 1.0, vcc
	v_cmp_eq_u32_e32 vcc, v56, v63
	s_nop 1
	v_cndmask_b32_e64 v49, 0, 1.0, vcc
	v_cmp_eq_u32_e32 vcc, v57, v63
	s_nop 1
	v_cndmask_b32_e64 v50, 0, 1.0, vcc
	v_cmp_eq_u32_e32 vcc, v58, v63
	s_nop 1
	v_cndmask_b32_e64 v51, 0, 1.0, vcc
	v_cmp_eq_u32_e32 vcc, v48, v63
	v_mov_b32_e32 v48, v0
	s_nop 0
	v_cndmask_b32_e64 v52, 0, 1.0, vcc
	v_cmp_eq_u32_e32 vcc, v53, v63
	s_nop 1
	v_cndmask_b32_e64 v53, 0, 1.0, vcc
	v_cmp_eq_u32_e32 vcc, v59, v63
	s_nop 1
	v_cndmask_b32_e64 v54, 0, 1.0, vcc
	v_cmp_eq_u32_e32 vcc, v60, v63
	s_nop 1
	v_cndmask_b32_e64 v55, 0, 1.0, vcc
	v_cmp_eq_u32_e32 vcc, v61, v63
	s_nop 1
	v_cndmask_b32_e64 v56, 0, 1.0, vcc
	v_cmp_eq_u32_e32 vcc, v62, v63
	s_nop 1
	v_cndmask_b32_e64 v57, 0, 1.0, vcc
	v_cmp_eq_u32_e32 vcc, v64, v63
	s_nop 1
	v_cndmask_b32_e64 v58, 0, 1.0, vcc
	v_cmp_eq_u32_e32 vcc, v65, v63
	s_nop 1
	v_cndmask_b32_e64 v59, 0, 1.0, vcc
	v_cmp_eq_u32_e32 vcc, v66, v63
	s_nop 1
	v_cndmask_b32_e64 v60, 0, 1.0, vcc
	v_cmp_eq_u32_e32 vcc, v67, v63
	s_nop 1
	v_cndmask_b32_e64 v61, 0, 1.0, vcc
	v_cmp_eq_u32_e32 vcc, v68, v63
	s_nop 1
	v_cndmask_b32_e64 v62, 0, 1.0, vcc
	v_cmp_eq_u32_e32 vcc, v69, v63
	s_nop 1
	v_cndmask_b32_e64 v63, 0, 1.0, vcc
	s_barrier
	s_branch .LBB0_720
; #define LAS __attribute__((address_space(3)))
; template <int role> __device__ __forceinline__ void ph_scan1m_r(Ctx& C) {
;     ...
;             f32x16 ya[2];
; #pragma unroll
;             for (int ct = 0; ct < 2; ++ct)
; #pragma unroll
;                 for (int e = 0; e < 16; ++e) ya[ct][e] = 0.f;
; #pragma unroll
;             for (int kt = 0; kt < 2; ++kt)
; #pragma unroll
;                 for (int sI = 0; sI < 2; ++sI) { const LAS bf16* ap = imKR + r31 * 72 + 32 * kt + 16 * sI + 4 * hh; const u32x2 lo = *(const LAS u32x2*)ap, hi = *(const LAS u32x2*)(ap + 8);
;                     u32x4 pa; pa.x = lo.x; pa.y = lo.y; pa.z = hi.x; pa.w = hi.y; const bf16x8 af = __builtin_bit_cast(bf16x8, pa);
; #pragma unroll
;                     for (int ct = 0; ct < 2; ++ct) { const f32x16& x = st[kt][ct];
;                         const bf16x8 bfr = pack8s(x[8 * sI], x[8 * sI + 1], x[8 * sI + 2], x[8 * sI + 3], x[8 * sI + 4], x[8 * sI + 5], x[8 * sI + 6], x[8 * sI + 7]);
;                         ya[ct] = __builtin_amdgcn_mfma_f32_32x32x16_bf16(af, bfr, ya[ct], 0, 0, 0); } }
;     ...
; #pragma unroll
;             for (int kt = 0; kt < 2; ++kt) { f32x4 gs[4];
; #pragma unroll
;                 for (int g = 0; g < 4; ++g) gs[g] = *(const LAS f32x4*)(gT + 32 * kt + 8 * g + 4 * hh);
;                 const bf16x8 au = *(const LAS bf16x8*)(imBGT + (32 * kt + r31) * 40 + 8 * hh); bf16x8 av; if (role) av = *(const LAS bf16x8*)(imBGT + (32 * kt + r31) * 40 + 16 + 8 * hh);
; #pragma unroll
;                 for (int ct = 0; ct < 2; ++ct) {
; #pragma unroll
;                     for (int e = 0; e < 16; ++e) st[kt][ct][e] *= gs[e >> 2][e & 3];
;                     st[kt][ct] = __builtin_amdgcn_mfma_f32_32x32x16_bf16(au, ufr[ct], st[kt][ct], 0, 0, 0);
;                     if (role) st[kt][ct] = __builtin_amdgcn_mfma_f32_32x32x16_bf16(av, vfr[ct], st[kt][ct], 0, 0, 0); } }
;             asm volatile("s_waitcnt lgkmcnt(0)" ::: "memory");
.LBB0_719:
	v_add_u32_e32 v88, s98, v161
	ds_read_b128 v[64:67], v88 offset:14400
	ds_read_b128 v[68:71], v88 offset:14432
	ds_read_b128 v[72:75], v88 offset:14336
	ds_read_b128 v[76:79], v88 offset:14368
	v_mad_u32_u24 v84, v158, s57, v88
	ds_read_b128 v[80:83], v84 offset:9216
	ds_read_b128 v[84:87], v84 offset:11776
	s_waitcnt lgkmcnt(4)
	v_pk_mul_f32 v[12:13], v[12:13], v[68:69]
	v_pk_mul_f32 v[8:9], v[8:9], v[64:65]
	s_waitcnt lgkmcnt(2)
	v_pk_mul_f32 v[4:5], v[4:5], v[76:77]
	v_pk_mul_f32 v[14:15], v[14:15], v[70:71]
	v_pk_mul_f32 v[10:11], v[10:11], v[66:67]
	v_pk_mul_f32 v[2:3], v[2:3], v[74:75]
	v_pk_mul_f32 v[28:29], v[28:29], v[68:69]
	v_pk_mul_f32 v[24:25], v[24:25], v[64:65]
	v_pk_mul_f32 v[20:21], v[20:21], v[76:77]
	v_pk_mul_f32 v[30:31], v[30:31], v[70:71]
	v_pk_mul_f32 v[26:27], v[26:27], v[66:67]
	v_pk_mul_f32 v[18:19], v[18:19], v[74:75]
	ds_read_b128 v[64:67], v88 offset:14528
	ds_read_b128 v[68:71], v88 offset:14560
	ds_read_b128 v[74:77], v88 offset:14464
	ds_read_b128 v[88:91], v88 offset:14496
	v_pk_mul_f32 v[6:7], v[6:7], v[78:79]
	v_pk_mul_f32 v[0:1], v[0:1], v[72:73]
	v_pk_mul_f32 v[22:23], v[22:23], v[78:79]
	v_pk_mul_f32 v[16:17], v[16:17], v[72:73]
	s_waitcnt lgkmcnt(2)
	v_pk_mul_f32 v[44:45], v[44:45], v[68:69]
	v_pk_mul_f32 v[40:41], v[40:41], v[64:65]
	s_waitcnt lgkmcnt(0)
	s_barrier
	v_pk_mul_f32 v[36:37], v[36:37], v[88:89]
	v_pk_mul_f32 v[46:47], v[46:47], v[70:71]
	v_pk_mul_f32 v[42:43], v[42:43], v[66:67]
	v_pk_mul_f32 v[38:39], v[38:39], v[90:91]
	v_pk_mul_f32 v[34:35], v[34:35], v[76:77]
	v_pk_mul_f32 v[32:33], v[32:33], v[74:75]
	v_pk_mul_f32 v[60:61], v[60:61], v[68:69]
	v_pk_mul_f32 v[56:57], v[56:57], v[64:65]
	v_pk_mul_f32 v[52:53], v[52:53], v[88:89]
	v_pk_mul_f32 v[62:63], v[62:63], v[70:71]
	v_pk_mul_f32 v[58:59], v[58:59], v[66:67]
	v_pk_mul_f32 v[54:55], v[54:55], v[90:91]
	v_pk_mul_f32 v[50:51], v[50:51], v[76:77]
	v_pk_mul_f32 v[48:49], v[48:49], v[74:75]
	v_mfma_f32_32x32x16_bf16 v[0:15], v[80:83], v[100:103], v[0:15]
	s_waitcnt lgkmcnt(0)
	s_add_i32 s62, s62, 16
	s_add_i32 s65, s65, -16
	s_cmpk_eq_i32 s62, 0x200
	v_mfma_f32_32x32x16_bf16 v[16:31], v[80:83], v[96:99], v[16:31]
	v_mfma_f32_32x32x16_bf16 v[32:47], v[84:87], v[100:103], v[32:47]
	v_mfma_f32_32x32x16_bf16 v[48:63], v[84:87], v[96:99], v[48:63]
	s_cbranch_scc1 .LBB0_715
.LBB0_720:
	s_waitcnt vmcnt(0) lgkmcnt(0)
	s_add_i32 s98, s42, 0x11400
	v_mov_b32_e32 v159, v124
	v_cmp_gt_u32_e32 vcc, 32, v159
	v_and_b32_e32 v158, 31, v159
	v_ashrrev_i32_e32 v160, 5, v159
	v_lshlrev_b32_e32 v161, 4, v160
	s_add_i32 s67, s25, s62
	s_add_i32 s2, s65, 16
	s_and_b64 s[0:1], s[28:29], exec
	s_cselect_b32 s36, s67, s2
	v_lshlrev_b32_e32 v96, 3, v160
	v_mov_b32_e32 v162, s98
	s_ashr_i32 s37, s36, 31
	v_mad_u32_u24 v163, v158, s54, v162
	s_barrier
	v_add_u32_e32 v104, v163, v96
	ds_read2_b64 v[64:67], v104 offset1:2
	v_cvt_pk_bf16_f32 v68, v0, v1
	v_cvt_pk_bf16_f32 v69, v2, v3
	v_cvt_pk_bf16_f32 v70, v4, v5
	v_cvt_pk_bf16_f32 v71, v6, v7
	s_nop 1
	s_waitcnt lgkmcnt(0)
	v_mfma_f32_32x32x16_bf16 v[80:95], v[64:67], v[68:71], 0
	v_cvt_pk_bf16_f32 v68, v16, v17
	v_cvt_pk_bf16_f32 v69, v18, v19
	v_cvt_pk_bf16_f32 v70, v20, v21
	v_cvt_pk_bf16_f32 v71, v22, v23
	s_nop 1
	ds_read2_b64 v[96:99], v104 offset0:4 offset1:6
	v_cvt_pk_bf16_f32 v100, v8, v9
	v_cvt_pk_bf16_f32 v101, v10, v11
	v_cvt_pk_bf16_f32 v102, v12, v13
	v_cvt_pk_bf16_f32 v103, v14, v15
	s_nop 1
	v_mfma_f32_32x32x16_bf16 v[64:79], v[64:67], v[68:71], 0
	s_waitcnt lgkmcnt(0)
	v_mfma_f32_32x32x16_bf16 v[80:95], v[96:99], v[100:103], v[80:95]
	v_cvt_pk_bf16_f32 v100, v24, v25
	v_cvt_pk_bf16_f32 v101, v26, v27
	v_cvt_pk_bf16_f32 v102, v28, v29
	v_cvt_pk_bf16_f32 v103, v30, v31
	s_nop 1
	s_nop 0
	v_mfma_f32_32x32x16_bf16 v[64:79], v[96:99], v[100:103], v[64:79]
	ds_read2_b64 v[96:99], v104 offset0:8 offset1:10
	v_cvt_pk_bf16_f32 v100, v32, v33
	v_cvt_pk_bf16_f32 v101, v34, v35
	v_cvt_pk_bf16_f32 v102, v36, v37
	v_cvt_pk_bf16_f32 v103, v38, v39
	s_nop 1
	s_waitcnt lgkmcnt(0)
	v_mfma_f32_32x32x16_bf16 v[80:95], v[96:99], v[100:103], v[80:95]
	v_cvt_pk_bf16_f32 v100, v48, v49
	v_cvt_pk_bf16_f32 v101, v50, v51
	v_cvt_pk_bf16_f32 v102, v52, v53
	v_cvt_pk_bf16_f32 v103, v54, v55
	s_nop 1
	s_nop 0
	v_mfma_f32_32x32x16_bf16 v[64:79], v[96:99], v[100:103], v[64:79]
	ds_read2_b64 v[96:99], v104 offset0:12 offset1:14
	v_cvt_pk_bf16_f32 v100, v40, v41
	v_cvt_pk_bf16_f32 v101, v42, v43
	v_cvt_pk_bf16_f32 v102, v44, v45
	v_cvt_pk_bf16_f32 v103, v46, v47
	s_nop 1
	s_waitcnt lgkmcnt(0)
	v_mfma_f32_32x32x16_bf16 v[80:95], v[96:99], v[100:103], v[80:95]
	v_cvt_pk_bf16_f32 v100, v56, v57
	v_cvt_pk_bf16_f32 v101, v58, v59
	v_cvt_pk_bf16_f32 v102, v60, v61
	v_cvt_pk_bf16_f32 v103, v62, v63
	s_nop 1
	s_nop 0
	v_mfma_f32_32x32x16_bf16 v[64:79], v[96:99], v[100:103], v[64:79]
	v_add_u32_e32 v112, 0x1000, v162
	ds_read2_b32 v[110:111], v112 offset0:164 offset1:200
	s_nop 7
	v_mov_b32_e32 v96, v80
	v_mov_b32_e32 v122, v80
	v_mov_b32_e32 v97, v64
	v_mov_b32_e32 v123, v64
	v_mov_b32_e32 v98, v81
	v_mov_b32_e32 v164, v81
	v_mov_b32_e32 v99, v65
	v_mov_b32_e32 v165, v65
	v_permlane32_swap_b32_e32 v96, v122
	v_permlane32_swap_b32_e32 v97, v123
	v_permlane32_swap_b32_e32 v98, v164
	v_permlane32_swap_b32_e32 v99, v165
	v_mov_b32_e32 v106, v82
	v_mov_b32_e32 v168, v82
	v_mov_b32_e32 v107, v66
	v_mov_b32_e32 v169, v66
	v_permlane32_swap_b32_e32 v106, v168
	s_nop 0
	v_permlane32_swap_b32_e32 v107, v169
	s_waitcnt lgkmcnt(0)
; #define LAS __attribute__((address_space(3)))
; template <int role> __device__ __forceinline__ void ph_scan1m_r(Ctx& C) {
;     ...
;             f32x2 u2[16];
; #pragma unroll
;             for (int e = 0; e < 4; ++e) {
;                 const auto a0 = __builtin_amdgcn_permlane32_swap(__float_as_uint(ya[0][e]), __float_as_uint(ya[0][e]), false, false), a1 = __builtin_amdgcn_permlane32_swap(__float_as_uint(ya[1][e]), __float_as_uint(ya[1][e]), false, false);
;                 const auto b0 = __builtin_amdgcn_permlane32_swap(__float_as_uint(ya[0][4 + e]), __float_as_uint(ya[0][4 + e]), false, false), b1 = __builtin_amdgcn_permlane32_swap(__float_as_uint(ya[1][4 + e]), __float_as_uint(ya[1][4 + e]), false, false);
;                 u2[e] = (f32x2){__uint_as_float(a0[0]), __uint_as_float(a1[0])}; u2[4 + e] = (f32x2){__uint_as_float(a0[1]), __uint_as_float(a1[1])};
;                 u2[8 + e] = (f32x2){__uint_as_float(b0[0]), __uint_as_float(b1[0])}; u2[12 + e] = (f32x2){__uint_as_float(b0[1]), __uint_as_float(b1[1])}; }
; #pragma unroll
;             for (int t = 1; t < 16; ++t) { f32x2 a = u2[t]; float clast = 0.f;
; #pragma unroll
;                 for (int q = 0; q < 4; ++q) { const int smin = q < 2 ? 8 * q : 8 * (q - 2) + 1;
;                     if (smin < t) { const f32x4 cf = *(const LAS f32x4*)(MT + t * 36 + 4 * q);
; #pragma unroll
;                         for (int e = 0; e < 4; ++e) { const int sl = 4 * q + e, st_ = sl < 8 ? 2 * sl : 2 * (sl - 8) + 1; if (st_ == t - 1) clast = cf[e]; else if (st_ < t) a += u2[st_] * cf[e]; } } }
;                 a += u2[t - 1] * clast;
;                 u2[t] = a; }
	v_pk_fma_f32 v[98:99], v[110:111], v[96:97], v[98:99] op_sel_hi:[0,1,1]
	v_mov_b32_e32 v110, v111
	v_pk_fma_f32 v[106:107], v[110:111], v[96:97], v[106:107] op_sel_hi:[0,1,1]
	ds_read_b32 v166, v162 offset:4928
	ds_read_b64 v[172:173], v162 offset:5040
	ds_read_b32 v174, v162 offset:5072
	ds_read2_b64 v[110:113], v112 offset0:136 offset1:140
	ds_read_b96 v[114:116], v162 offset:5328
	v_mov_b32_e32 v108, v83
	v_mov_b32_e32 v170, v83
	v_mov_b32_e32 v109, v67
	v_mov_b32_e32 v171, v67
	v_permlane32_swap_b32_e32 v108, v170
	s_nop 0
	v_permlane32_swap_b32_e32 v109, v171
	s_waitcnt lgkmcnt(4)
	v_pk_fma_f32 v[106:107], v[98:99], v[166:167], v[106:107] op_sel_hi:[1,0,1]
	s_waitcnt lgkmcnt(3)
	v_pk_fma_f32 v[108:109], v[172:173], v[96:97], v[108:109] op_sel_hi:[0,1,1]
	s_waitcnt lgkmcnt(1)
	v_pk_fma_f32 v[122:123], v[110:111], v[96:97], v[122:123] op_sel_hi:[0,1,1]
	v_pk_fma_f32 v[108:109], v[98:99], v[174:175], v[108:109] op_sel_hi:[1,0,1]
	v_pk_fma_f32 v[110:111], v[106:107], v[110:111], v[122:123] op_sel:[0,1,0]
	ds_read_b64 v[122:123], v162 offset:5360
	v_pk_fma_f32 v[108:109], v[172:173], v[106:107], v[108:109] op_sel:[1,0,0]
	v_pk_fma_f32 v[110:111], v[98:99], v[112:113], v[110:111] op_sel_hi:[1,0,1]
	ds_read_b96 v[172:174], v162 offset:5648
	v_pk_fma_f32 v[110:111], v[112:113], v[108:109], v[110:111] op_sel:[1,0,0]
	s_waitcnt lgkmcnt(2)
	v_pk_fma_f32 v[112:113], v[114:115], v[96:97], v[164:165] op_sel_hi:[0,1,1]
	ds_read_b96 v[164:166], v162 offset:5472
	v_pk_fma_f32 v[112:113], v[106:107], v[114:115], v[112:113] op_sel:[0,1,0]
	v_mov_b32_e32 v114, v116
	s_waitcnt lgkmcnt(2)
	v_pk_fma_f32 v[112:113], v[98:99], v[122:123], v[112:113] op_sel_hi:[1,0,1]
	v_mov_b32_e32 v176, v84
	v_pk_fma_f32 v[112:113], v[108:109], v[122:123], v[112:113] op_sel:[0,1,0]
	s_waitcnt lgkmcnt(0)
	v_pk_fma_f32 v[122:123], v[164:165], v[96:97], v[168:169] op_sel_hi:[0,1,1]
	v_pk_fma_f32 v[112:113], v[114:115], v[110:111], v[112:113] op_sel_hi:[0,1,1]
	ds_read_b96 v[114:116], v162 offset:5504
	v_pk_fma_f32 v[122:123], v[106:107], v[164:165], v[122:123] op_sel:[0,1,0]
	v_mov_b32_e32 v164, v166
	v_pk_fma_f32 v[122:123], v[164:165], v[110:111], v[122:123] op_sel_hi:[0,1,1]
	ds_read_b128 v[164:167], v162 offset:5616
	s_waitcnt lgkmcnt(1)
	v_pk_fma_f32 v[122:123], v[98:99], v[114:115], v[122:123] op_sel_hi:[1,0,1]
	v_mov_b32_e32 v120, v84
	v_pk_fma_f32 v[114:115], v[108:109], v[114:115], v[122:123] op_sel:[0,1,0]
	v_mov_b32_e32 v177, v68
	v_pk_fma_f32 v[114:115], v[116:117], v[112:113], v[114:115] op_sel_hi:[0,1,1]
	s_waitcnt lgkmcnt(0)
	v_pk_fma_f32 v[116:117], v[164:165], v[96:97], v[170:171] op_sel_hi:[0,1,1]
	v_pk_fma_f32 v[116:117], v[106:107], v[164:165], v[116:117] op_sel:[0,1,0]
	ds_read_b128 v[168:171], v162 offset:5760
	v_pk_fma_f32 v[116:117], v[110:111], v[166:167], v[116:117] op_sel_hi:[1,0,1]
	v_mov_b32_e32 v121, v68
	v_pk_fma_f32 v[116:117], v[98:99], v[172:173], v[116:117] op_sel_hi:[1,0,1]
	v_mov_b32_e32 v122, v174
	v_pk_fma_f32 v[116:117], v[108:109], v[172:173], v[116:117] op_sel:[0,1,0]
	v_permlane32_swap_b32_e32 v176, v120
	v_permlane32_swap_b32_e32 v177, v121
	v_pk_fma_f32 v[116:117], v[122:123], v[112:113], v[116:117] op_sel_hi:[0,1,1]
	v_mov_b32_e32 v122, v167
	v_pk_fma_f32 v[116:117], v[122:123], v[114:115], v[116:117] op_sel_hi:[0,1,1]
	s_waitcnt lgkmcnt(0)
	v_pk_fma_f32 v[122:123], v[168:169], v[96:97], v[176:177] op_sel_hi:[0,1,1]
	ds_read_b128 v[164:167], v162 offset:5792
	v_pk_fma_f32 v[122:123], v[106:107], v[168:169], v[122:123] op_sel:[0,1,0]
	v_mov_b32_e32 v168, v171
	v_pk_fma_f32 v[122:123], v[110:111], v[170:171], v[122:123] op_sel_hi:[1,0,1]
	v_mov_b32_e32 v178, v85
	v_pk_fma_f32 v[122:123], v[168:169], v[114:115], v[122:123] op_sel_hi:[0,1,1]
	ds_read_b128 v[168:171], v162 offset:5904
	s_waitcnt lgkmcnt(1)
	v_pk_fma_f32 v[122:123], v[98:99], v[164:165], v[122:123] op_sel_hi:[1,0,1]
	v_mov_b32_e32 v118, v85
	v_mov_b32_e32 v179, v69
	v_mov_b32_e32 v119, v69
	v_pk_fma_f32 v[122:123], v[108:109], v[164:165], v[122:123] op_sel:[0,1,0]
	v_permlane32_swap_b32_e32 v178, v118
	v_permlane32_swap_b32_e32 v179, v119
	v_pk_fma_f32 v[122:123], v[112:113], v[166:167], v[122:123] op_sel_hi:[1,0,1]
	v_mov_b32_e32 v164, v167
	v_pk_fma_f32 v[122:123], v[164:165], v[116:117], v[122:123] op_sel_hi:[0,1,1]
	s_waitcnt lgkmcnt(0)
	v_pk_fma_f32 v[164:165], v[168:169], v[96:97], v[178:179] op_sel_hi:[0,1,1]
	v_pk_fma_f32 v[164:165], v[106:107], v[168:169], v[164:165] op_sel:[0,1,0]
	v_mov_b32_e32 v180, v86
	v_pk_fma_f32 v[168:169], v[110:111], v[170:171], v[164:165] op_sel_hi:[1,0,1]
	ds_read_b128 v[164:167], v162 offset:5936
	v_mov_b32_e32 v170, v171
	v_pk_fma_f32 v[172:173], v[170:171], v[114:115], v[168:169] op_sel_hi:[0,1,1]
	v_add_u32_e32 v168, 0x1400, v162
	ds_read2_b32 v[174:175], v168 offset0:200 offset1:236
	ds_read_b128 v[168:171], v162 offset:6048
	s_waitcnt lgkmcnt(2)
	v_pk_fma_f32 v[172:173], v[98:99], v[164:165], v[172:173] op_sel_hi:[1,0,1]
	v_mov_b32_e32 v102, v86
	v_pk_fma_f32 v[164:165], v[108:109], v[164:165], v[172:173] op_sel:[0,1,0]
	v_mov_b32_e32 v181, v70
	v_mov_b32_e32 v103, v70
	v_pk_fma_f32 v[164:165], v[112:113], v[166:167], v[164:165] op_sel_hi:[1,0,1]
	v_mov_b32_e32 v166, v167
	v_permlane32_swap_b32_e32 v180, v102
	v_permlane32_swap_b32_e32 v181, v103
	v_pk_fma_f32 v[164:165], v[166:167], v[116:117], v[164:165] op_sel_hi:[0,1,1]
	s_waitcnt lgkmcnt(1)
	v_pk_fma_f32 v[176:177], v[174:175], v[122:123], v[164:165] op_sel_hi:[0,1,1]
	s_waitcnt lgkmcnt(0)
; #define LAS __attribute__((address_space(3)))
; template <int role> __device__ __forceinline__ void ph_scan1m_r(Ctx& C) {
;     ...
; #pragma unroll
;             for (int t = 1; t < 16; ++t) { f32x2 a = u2[t]; float clast = 0.f;
; #pragma unroll
;                 for (int q = 0; q < 4; ++q) { const int smin = q < 2 ? 8 * q : 8 * (q - 2) + 1;
;                     if (smin < t) { const f32x4 cf = *(const LAS f32x4*)(MT + t * 36 + 4 * q);
; #pragma unroll
;                         for (int e = 0; e < 4; ++e) { const int sl = 4 * q + e, st_ = sl < 8 ? 2 * sl : 2 * (sl - 8) + 1; if (st_ == t - 1) clast = cf[e]; else if (st_ < t) a += u2[st_] * cf[e]; } } }
;                 a += u2[t - 1] * clast;
;                 u2[t] = a; }
	v_pk_fma_f32 v[164:165], v[168:169], v[96:97], v[180:181] op_sel_hi:[0,1,1]
	v_pk_fma_f32 v[164:165], v[106:107], v[168:169], v[164:165] op_sel:[0,1,0]
	ds_read_b32 v172, v162 offset:6096
	v_pk_fma_f32 v[168:169], v[110:111], v[170:171], v[164:165] op_sel_hi:[1,0,1]
	ds_read_b128 v[164:167], v162 offset:6080
	v_mov_b32_e32 v170, v171
	v_pk_fma_f32 v[168:169], v[114:115], v[170:171], v[168:169] op_sel_hi:[1,0,1]
	v_mov_b32_e32 v170, v175
	v_pk_fma_f32 v[168:169], v[170:171], v[122:123], v[168:169] op_sel_hi:[0,1,1]
	s_waitcnt lgkmcnt(0)
	v_pk_fma_f32 v[168:169], v[98:99], v[164:165], v[168:169] op_sel_hi:[1,0,1]
	v_mov_b32_e32 v182, v87
	v_pk_fma_f32 v[164:165], v[108:109], v[164:165], v[168:169] op_sel:[0,1,0]
	ds_read_b128 v[168:171], v162 offset:6192
	v_mov_b32_e32 v100, v87
	v_mov_b32_e32 v183, v71
	v_mov_b32_e32 v101, v71
	v_pk_fma_f32 v[164:165], v[112:113], v[166:167], v[164:165] op_sel_hi:[1,0,1]
	v_mov_b32_e32 v166, v167
	v_permlane32_swap_b32_e32 v182, v100
	v_permlane32_swap_b32_e32 v183, v101
	v_pk_fma_f32 v[164:165], v[116:117], v[166:167], v[164:165] op_sel_hi:[1,0,1]
	s_nop 0
	v_pk_fma_f32 v[178:179], v[172:173], v[176:177], v[164:165] op_sel_hi:[0,1,1]
	ds_read_b64 v[172:173], v162 offset:6208
	s_waitcnt lgkmcnt(1)
	v_pk_fma_f32 v[164:165], v[168:169], v[96:97], v[182:183] op_sel_hi:[0,1,1]
	v_pk_fma_f32 v[164:165], v[106:107], v[168:169], v[164:165] op_sel:[0,1,0]
	s_nop 0
	v_pk_fma_f32 v[168:169], v[110:111], v[170:171], v[164:165] op_sel_hi:[1,0,1]
	ds_read_b128 v[164:167], v162 offset:6224
	v_mov_b32_e32 v170, v171
	v_pk_fma_f32 v[168:169], v[114:115], v[170:171], v[168:169] op_sel_hi:[1,0,1]
	ds_read_b32 v170, v162 offset:6240
	s_waitcnt lgkmcnt(2)
	v_pk_fma_f32 v[168:169], v[122:123], v[172:173], v[168:169] op_sel_hi:[1,0,1]
	s_waitcnt lgkmcnt(1)
	v_mov_b32_e32 v174, v167
	v_pk_fma_f32 v[168:169], v[98:99], v[164:165], v[168:169] op_sel_hi:[1,0,1]
	s_nop 0
	v_pk_fma_f32 v[164:165], v[108:109], v[164:165], v[168:169] op_sel:[0,1,0]
	s_nop 0
	v_pk_fma_f32 v[168:169], v[112:113], v[166:167], v[164:165] op_sel_hi:[1,0,1]
	ds_read_b128 v[164:167], v162 offset:6336
	v_pk_fma_f32 v[168:169], v[116:117], v[174:175], v[168:169] op_sel_hi:[1,0,1]
	s_waitcnt lgkmcnt(1)
	v_pk_fma_f32 v[168:169], v[170:171], v[176:177], v[168:169] op_sel_hi:[0,1,1]
	v_pk_fma_f32 v[180:181], v[172:173], v[178:179], v[168:169] op_sel:[1,0,0]
	v_add_u32_e32 v172, 0x1800, v162
	ds_read2_b64 v[172:175], v172 offset0:26 offset1:30
	ds_read_b128 v[168:171], v162 offset:6368
	s_waitcnt lgkmcnt(2)
	v_pk_fma_f32 v[120:121], v[164:165], v[96:97], v[120:121] op_sel_hi:[0,1,1]
	v_pk_fma_f32 v[120:121], v[106:107], v[164:165], v[120:121] op_sel:[0,1,0]
	v_mov_b32_e32 v164, v167
	v_pk_fma_f32 v[120:121], v[110:111], v[166:167], v[120:121] op_sel_hi:[1,0,1]
	s_nop 0
	v_pk_fma_f32 v[120:121], v[114:115], v[164:165], v[120:121] op_sel_hi:[1,0,1]
	ds_read_b128 v[164:167], v162 offset:6480
	s_waitcnt lgkmcnt(2)
	v_pk_fma_f32 v[120:121], v[122:123], v[172:173], v[120:121] op_sel_hi:[1,0,1]
	s_nop 0
	v_pk_fma_f32 v[120:121], v[172:173], v[178:179], v[120:121] op_sel:[1,0,0]
	s_waitcnt lgkmcnt(1)
	v_pk_fma_f32 v[120:121], v[98:99], v[168:169], v[120:121] op_sel_hi:[1,0,1]
	s_nop 0
	v_pk_fma_f32 v[120:121], v[108:109], v[168:169], v[120:121] op_sel:[0,1,0]
	v_mov_b32_e32 v168, v171
	v_pk_fma_f32 v[120:121], v[112:113], v[170:171], v[120:121] op_sel_hi:[1,0,1]
	s_nop 0
	v_pk_fma_f32 v[120:121], v[116:117], v[168:169], v[120:121] op_sel_hi:[1,0,1]
	ds_read_b96 v[168:170], v162 offset:6496
	s_waitcnt lgkmcnt(1)
	v_pk_fma_f32 v[118:119], v[164:165], v[96:97], v[118:119] op_sel_hi:[0,1,1]
	v_pk_fma_f32 v[120:121], v[176:177], v[174:175], v[120:121] op_sel_hi:[1,0,1]
	v_pk_fma_f32 v[118:119], v[106:107], v[164:165], v[118:119] op_sel:[0,1,0]
	v_pk_fma_f32 v[172:173], v[174:175], v[180:181], v[120:121] op_sel:[1,0,0]
	v_pk_fma_f32 v[164:165], v[110:111], v[166:167], v[118:119] op_sel_hi:[1,0,1]
	ds_read_b128 v[118:121], v162 offset:6512
	v_mov_b32_e32 v166, v167
	v_pk_fma_f32 v[164:165], v[114:115], v[166:167], v[164:165] op_sel_hi:[1,0,1]
	ds_read_b64 v[166:167], v162 offset:6528
	s_waitcnt lgkmcnt(2)
	v_pk_fma_f32 v[164:165], v[122:123], v[168:169], v[164:165] op_sel_hi:[1,0,1]
	s_nop 0
	v_pk_fma_f32 v[164:165], v[178:179], v[168:169], v[164:165] op_sel:[0,1,0]
	s_waitcnt lgkmcnt(1)
	v_pk_fma_f32 v[164:165], v[98:99], v[118:119], v[164:165] op_sel_hi:[1,0,1]
	s_nop 0
	v_pk_fma_f32 v[118:119], v[108:109], v[118:119], v[164:165] op_sel:[0,1,0]
	s_nop 0
	v_pk_fma_f32 v[118:119], v[112:113], v[120:121], v[118:119] op_sel_hi:[1,0,1]
	v_mov_b32_e32 v120, v121
	v_pk_fma_f32 v[118:119], v[116:117], v[120:121], v[118:119] op_sel_hi:[1,0,1]
	s_waitcnt lgkmcnt(0)
	v_pk_fma_f32 v[164:165], v[176:177], v[166:167], v[118:119] op_sel_hi:[1,0,1]
	ds_read_b128 v[118:121], v162 offset:6624
	v_pk_fma_f32 v[164:165], v[166:167], v[180:181], v[164:165] op_sel:[1,0,0]
	v_mov_b32_e32 v166, v170
	v_pk_fma_f32 v[168:169], v[166:167], v[172:173], v[164:165] op_sel_hi:[0,1,1]
	ds_read_b96 v[164:166], v162 offset:6640
	s_waitcnt lgkmcnt(1)
	v_pk_fma_f32 v[102:103], v[118:119], v[96:97], v[102:103] op_sel_hi:[0,1,1]
	v_pk_fma_f32 v[102:103], v[106:107], v[118:119], v[102:103] op_sel:[0,1,0]
	v_mov_b32_e32 v118, v121
	v_pk_fma_f32 v[102:103], v[110:111], v[120:121], v[102:103] op_sel_hi:[1,0,1]
	s_nop 0
	v_pk_fma_f32 v[102:103], v[114:115], v[118:119], v[102:103] op_sel_hi:[1,0,1]
	ds_read_b128 v[118:121], v162 offset:6656
	s_waitcnt lgkmcnt(1)
; #define LAS __attribute__((address_space(3)))
; __device__ __forceinline__ unsigned cvt_pk_bf16(float lo, float hi) { unsigned r; asm volatile("v_cvt_pk_bf16_f32 %0, %1, %2" : "=v"(r) : "v"(lo), "v"(hi)); return r; }
; template <int role> __device__ __forceinline__ void ph_scan1m_r(Ctx& C) {
;     ...
;             bf16x8 ufr[2];
;             ufr[0] = pack8s(hh ? u2[1].x : u2[0].x, hh ? u2[3].x : u2[2].x, hh ? u2[5].x : u2[4].x, hh ? u2[7].x : u2[6].x, hh ? u2[9].x : u2[8].x, hh ? u2[11].x : u2[10].x, hh ? u2[13].x : u2[12].x, hh ? u2[15].x : u2[14].x);
;             ufr[1] = pack8s(hh ? u2[1].y : u2[0].y, hh ? u2[3].y : u2[2].y, hh ? u2[5].y : u2[4].y, hh ? u2[7].y : u2[6].y, hh ? u2[9].y : u2[8].y, hh ? u2[11].y : u2[10].y, hh ? u2[13].y : u2[12].y, hh ? u2[15].y : u2[14].y);
;             __builtin_amdgcn_sched_barrier(0);
;             { const f32x4 m0 = *(const LAS f32x4*)(MT + r31 * 36 + 8 * hh), m1 = *(const LAS f32x4*)(MT + r31 * 36 + 4 + 8 * hh); const bf16x8 af = pack8s(m0[0], m0[1], m0[2], m0[3], m1[0], m1[1], m1[2], m1[3]);
; #pragma unroll
;               for (int ct = 0; ct < 2; ++ct) ya[ct] = __builtin_amdgcn_mfma_f32_32x32x16_bf16(af, ufr[ct], ya[ct], 0, 0, 0); }
;             { LAS bf16* ys = (LAS bf16*)MT;
; #pragma unroll
;               for (int ct = 0; ct < 2; ++ct)
; #pragma unroll
;                   for (int e = 0; e < 8; e += 2) { const unsigned pw = pg8::cvt_pk_bf16(ya[ct][8 + e], ya[ct][9 + e]); const int t = (e & 3) + 4 * hh + 8 * (e >> 2); LAS bf16* d = ys + t * 72 + 32 * ct + r31; d[0] = (bf16)pw; d[72] = (bf16)(pw >> 16); }
;               asm volatile("s_waitcnt lgkmcnt(0)" ::: "memory");
; #pragma unroll
;               for (int i = 0; i < 2; ++i) { const int t = (lane >> 3) + 8 * i; const u32x4 w = *(const LAS u32x4*)(ys + t * 72 + 8 * (lane & 7)); *(u32x4*)(g_out + zoff + rowu + (long)t * dix + 8 * (lane & 7)) = w; }
;               asm volatile("s_waitcnt lgkmcnt(0)" ::: "memory"); }
	v_pk_fma_f32 v[102:103], v[122:123], v[164:165], v[102:103] op_sel_hi:[1,0,1]
	s_nop 0
	v_pk_fma_f32 v[102:103], v[178:179], v[164:165], v[102:103] op_sel:[0,1,0]
	v_mov_b32_e32 v164, v166
	v_pk_fma_f32 v[102:103], v[164:165], v[172:173], v[102:103] op_sel_hi:[0,1,1]
	ds_read_b96 v[164:166], v162 offset:6672
	s_waitcnt lgkmcnt(1)
	v_pk_fma_f32 v[102:103], v[98:99], v[118:119], v[102:103] op_sel_hi:[1,0,1]
	s_nop 0
	v_pk_fma_f32 v[102:103], v[108:109], v[118:119], v[102:103] op_sel:[0,1,0]
	v_mov_b32_e32 v118, v121
	v_pk_fma_f32 v[102:103], v[112:113], v[120:121], v[102:103] op_sel_hi:[1,0,1]
	s_nop 0
	v_pk_fma_f32 v[102:103], v[116:117], v[118:119], v[102:103] op_sel_hi:[1,0,1]
	ds_read_b128 v[118:121], v162 offset:6768
	s_waitcnt lgkmcnt(1)
	v_pk_fma_f32 v[102:103], v[176:177], v[164:165], v[102:103] op_sel_hi:[1,0,1]
	s_nop 0
	v_pk_fma_f32 v[102:103], v[180:181], v[164:165], v[102:103] op_sel:[0,1,0]
	v_mov_b32_e32 v164, v166
	v_pk_fma_f32 v[170:171], v[164:165], v[168:169], v[102:103] op_sel_hi:[0,1,1]
	ds_read_b128 v[164:167], v162 offset:6784
	s_waitcnt lgkmcnt(1)
	v_pk_fma_f32 v[100:101], v[118:119], v[96:97], v[100:101] op_sel_hi:[0,1,1]
	v_pk_fma_f32 v[100:101], v[106:107], v[118:119], v[100:101] op_sel:[0,1,0]
	v_mov_b32_e32 v102, v121
	v_pk_fma_f32 v[100:101], v[110:111], v[120:121], v[100:101] op_sel_hi:[1,0,1]
	v_cndmask_b32_e32 v96, v98, v96, vcc
	v_pk_fma_f32 v[118:119], v[114:115], v[102:103], v[100:101] op_sel_hi:[1,0,1]
	ds_read_b128 v[100:103], v162 offset:6800
	s_waitcnt lgkmcnt(1)
	v_pk_fma_f32 v[118:119], v[122:123], v[164:165], v[118:119] op_sel_hi:[1,0,1]
	v_cndmask_b32_e32 v107, v109, v107, vcc
	v_pk_fma_f32 v[118:119], v[178:179], v[164:165], v[118:119] op_sel:[0,1,0]
	s_nop 0
	v_pk_fma_f32 v[164:165], v[166:167], v[172:173], v[118:119] op_sel_hi:[0,1,1]
	ds_read_b96 v[118:120], v162 offset:6816
	s_waitcnt lgkmcnt(1)
	v_pk_fma_f32 v[164:165], v[98:99], v[100:101], v[164:165] op_sel_hi:[1,0,1]
	v_cndmask_b32_e32 v98, v108, v106, vcc
	v_pk_fma_f32 v[100:101], v[108:109], v[100:101], v[164:165] op_sel:[0,1,0]
	v_cndmask_b32_e32 v106, v112, v110, vcc
	v_pk_fma_f32 v[100:101], v[112:113], v[102:103], v[100:101] op_sel_hi:[1,0,1]
	v_mov_b32_e32 v102, v103
	v_pk_fma_f32 v[100:101], v[116:117], v[102:103], v[100:101] op_sel_hi:[1,0,1]
	s_waitcnt lgkmcnt(0)
	v_mov_b32_e32 v102, v120
	v_pk_fma_f32 v[100:101], v[176:177], v[118:119], v[100:101] op_sel_hi:[1,0,1]
	v_cndmask_b32_e32 v108, v116, v114, vcc
	v_pk_fma_f32 v[100:101], v[180:181], v[118:119], v[100:101] op_sel:[0,1,0]
	v_cndmask_b32_e32 v110, v176, v122, vcc
	v_pk_fma_f32 v[100:101], v[102:103], v[168:169], v[100:101] op_sel_hi:[0,1,1]
	v_mov_b32_e32 v102, v167
	v_pk_fma_f32 v[118:119], v[102:103], v[170:171], v[100:101] op_sel_hi:[0,1,1]
	v_cndmask_b32_e32 v112, v180, v178, vcc
	v_cndmask_b32_e32 v114, v168, v172, vcc
	v_cndmask_b32_e32 v116, v118, v170, vcc
	v_cvt_pk_bf16_f32 v100, v96, v98
	v_cvt_pk_bf16_f32 v101, v106, v108
	v_cvt_pk_bf16_f32 v102, v110, v112
	v_cvt_pk_bf16_f32 v103, v114, v116
	s_nop 1
	v_cndmask_b32_e32 v106, v99, v97, vcc
	v_cndmask_b32_e32 v108, v113, v111, vcc
	v_cndmask_b32_e32 v109, v117, v115, vcc
	v_cndmask_b32_e32 v110, v177, v123, vcc
	v_cndmask_b32_e32 v111, v181, v179, vcc
	v_cndmask_b32_e32 v112, v169, v173, vcc
	v_cndmask_b32_e32 v113, v119, v171, vcc
	v_cvt_pk_bf16_f32 v96, v106, v107
	v_cvt_pk_bf16_f32 v97, v108, v109
	v_cvt_pk_bf16_f32 v98, v110, v111
	v_cvt_pk_bf16_f32 v99, v112, v113
	s_nop 1
	v_mad_u64_u32 v[110:111], s[0:1], v160, 24, v[104:105]
	ds_read_b128 v[106:109], v110 offset:4608
	ds_read_b128 v[110:113], v110 offset:4624
	s_lshl_b64 s[0:1], s[36:37], 11
	s_add_u32 s0, s63, s0
	s_addc_u32 s1, s64, s1
	s_waitcnt lgkmcnt(0)
	s_barrier
	v_cvt_pk_bf16_f32 v114, v106, v107
	v_cvt_pk_bf16_f32 v115, v108, v109
	v_cvt_pk_bf16_f32 v116, v110, v111
	v_cvt_pk_bf16_f32 v117, v112, v113
	s_nop 1
	s_nop 0
	v_mfma_f32_32x32x16_bf16 v[80:95], v[114:117], v[100:103], v[80:95]
	v_mfma_f32_32x32x16_bf16 v[64:79], v[114:117], v[96:99], v[64:79]
	s_nop 10
	v_mul_i32_i24_e32 v80, 0xffffff72, v158
	v_mul_lo_u32 v81, v160, s56
	v_add3_u32 v80, v163, v80, v81
	v_add_u32_e32 v80, 0xfffeec00, v80
	v_cvt_pk_bf16_f32 v64, v88, v89
	ds_write_b16 v80, v64 offset:4608
	ds_write_b16_d16_hi v80, v64 offset:4752
	v_cvt_pk_bf16_f32 v64, v90, v91
	ds_write_b16 v80, v64 offset:4896
	ds_write_b16_d16_hi v80, v64 offset:5040
	v_cvt_pk_bf16_f32 v64, v92, v93
	ds_write_b16 v80, v64 offset:5760
	ds_write_b16_d16_hi v80, v64 offset:5904
	v_cvt_pk_bf16_f32 v64, v94, v95
	ds_write_b16 v80, v64 offset:6048
	ds_write_b16_d16_hi v80, v64 offset:6192
	v_cvt_pk_bf16_f32 v64, v72, v73
	ds_write_b16 v80, v64 offset:4672
	ds_write_b16_d16_hi v80, v64 offset:4816
	v_cvt_pk_bf16_f32 v64, v74, v75
	ds_write_b16 v80, v64 offset:4960
	ds_write_b16_d16_hi v80, v64 offset:5104
	v_cvt_pk_bf16_f32 v64, v76, v77
	ds_write_b16 v80, v64 offset:5824
	ds_write_b16_d16_hi v80, v64 offset:5968
	v_cvt_pk_bf16_f32 v64, v78, v79
	ds_write_b16 v80, v64 offset:6112
	ds_write_b16_d16_hi v80, v64 offset:6256
	v_ashrrev_i32_e32 v76, 3, v159
	v_lshlrev_b32_e32 v64, 4, v159
	v_and_b32_e32 v104, 0x70, v64
	v_mul_lo_u32 v64, v76, s54
	s_waitcnt lgkmcnt(0)
	v_add3_u32 v70, s42, v104, v64
	ds_read_b128 v[64:67], v70 offset:4608
	v_ashrrev_i32_e32 v68, 31, v76
	v_lshl_add_u64 v[72:73], s[0:1], 0, v[104:105]
	v_mul_lo_u32 v71, s30, v68
	v_mul_lo_u32 v74, s31, v76
	v_mad_u64_u32 v[68:69], s[0:1], s30, v76, 0
	v_add3_u32 v69, v69, v71, v74
	v_lshl_add_u64 v[74:75], v[68:69], 1, v[72:73]
	ds_read_b128 v[68:71], v70 offset:5760
	s_waitcnt lgkmcnt(1)
	global_store_dwordx4 v[74:75], v[64:67], off
	s_nop 1
	v_add_u32_e32 v64, 8, v76
	v_ashrrev_i32_e32 v65, 31, v64
	v_mul_lo_u32 v66, s30, v65
	v_mul_lo_u32 v67, s31, v64
	v_mad_u64_u32 v[64:65], s[0:1], s30, v64, 0
	v_add3_u32 v65, v65, v66, v67
	v_lshl_add_u64 v[64:65], v[64:65], 1, v[72:73]
	s_waitcnt lgkmcnt(0)
	global_store_dwordx4 v[64:65], v[68:71], off
	s_waitcnt lgkmcnt(0)
	s_branch .LBB0_719
